# v87 + gemm128g tails (G1/G4) via whole-line LDS-DMA, 2 stages of 32 KB
# baseline (speedup 1.0000x reference)
.LBB1_65:
	v_readlane_b32 s4, v242, 0
	s_lshl_b32 s5, s2, 3
	s_and_b32 s6, s4, 7
	s_or_b32 s5, s6, s5
	s_mul_i32 s5, s5, s55
	s_ashr_i32 s4, s4, 3
	s_add_i32 s5, s5, s4
	s_cmp_gt_i32 s5, 63
	s_mov_b64 s[40:41], -1
	s_cbranch_scc1 .LBB1_64
	s_ashr_i32 s4, s5, 31
	s_lshr_b32 s4, s4, 25
	s_add_i32 s6, s5, s4
	s_ashr_i32 s4, s6, 7
	s_lshl_b32 s7, s4, 3
	s_sub_i32 s4, 4, s7
	s_min_u32 s8, s4, 8
	v_cvt_f32_ubyte0_e32 v0, s8
	v_rcp_iflag_f32_e32 v0, v0
	s_sub_i32 s10, 0, s8
	s_and_b32 s6, s6, 0xffffff80
	s_sub_i32 s5, s5, s6
	v_mul_f32_e32 v0, 0x4f7ffffe, v0
	v_cvt_u32_f32_e32 v0, v0
	s_abs_i32 s9, s5
	s_ashr_i32 s6, s5, 31
	s_waitcnt lgkmcnt(0)
	v_mov_b32_e32 v2, v162
	v_readfirstlane_b32 s11, v0
	s_mul_i32 s10, s10, s11
	s_mul_hi_u32 s10, s11, s10
	s_add_i32 s11, s11, s10
	s_mul_hi_u32 s10, s9, s11
	s_mul_i32 s11, s10, s8
	s_sub_i32 s9, s9, s11
	s_add_i32 s11, s10, 1
	s_sub_i32 s12, s9, s8
	s_cmp_ge_u32 s9, s8
	s_cselect_b32 s10, s11, s10
	s_cselect_b32 s9, s12, s9
	s_add_i32 s11, s10, 1
	s_cmp_ge_u32 s9, s8
	s_cselect_b32 s9, s11, s10
	s_xor_b32 s9, s9, s6
	s_sub_i32 s9, s9, s6
	s_mul_i32 s6, s9, s8
	s_sub_i32 s5, s5, s6
	s_add_i32 s5, s5, s7
	s_lshl_b32 s6, s5, 7
	v_readfirstlane_b32 s10, v2
	s_ashr_i32 s7, s10, 6
	v_bfe_u32 v0, v2, 2, 4
	v_lshrrev_b32_e32 v1, 3, v2
	s_addk_i32 s6, 0x4000
	s_lshl_b32 s5, s9, 7
	v_and_b32_e32 v1, 6, v1
	s_movk_i32 s9, 0x78
	v_lshl_or_b32 v4, s7, 5, v0
	v_lshrrev_b32_e64 v1, v1, s9
	v_add_u32_e32 v0, s6, v4
	v_xor_b32_e32 v3, v1, v2
	v_ashrrev_i32_e32 v1, 31, v0
	v_lshlrev_b64 v[0:1], 11, v[0:1]
	v_lshlrev_b32_e32 v3, 4, v3
	s_waitcnt lgkmcnt(0)
	s_load_dwordx16 s[80:95], s[0:1], 0xc0
	v_lshl_add_u64 v[0:1], s[74:75], 0, v[0:1]
	v_and_b32_e32 v128, 48, v3
	v_lshl_add_u64 v[64:65], v[0:1], 0, v[128:129]
	v_add_u32_e32 v0, s5, v4
	v_ashrrev_i32_e32 v1, 31, v0
	s_lshl_b32 s7, s7, 11
	v_lshlrev_b64 v[0:1], 11, v[0:1]
	s_add_i32 s7, s7, 16
	s_waitcnt lgkmcnt(0)
	v_lshl_add_u64 v[0:1], s[92:93], 0, v[0:1]
	s_mov_b32 m0, s7
	v_lshl_add_u64 v[66:67], v[0:1], 0, v[128:129]
	s_barrier
	v_lshl_add_u64 v[0:1], v[64:65], 0, s[34:35]
	s_add_i32 m0, s7, 0x400
	s_mov_b64 s[12:13], 0x8040
	s_add_i32 m0, s7, 0x2000
	v_lshl_add_u64 v[0:1], v[66:67], 0, s[34:35]
	s_add_i32 m0, s7, 0x2400
	v_bfe_u32 v68, v2, 4, 2
	v_lshl_add_u64 v[0:1], v[64:65], 0, 64
	s_add_i32 m0, s7, 0x4000
	v_and_b32_e32 v69, 15, v2
	v_lshl_add_u64 v[0:1], v[64:65], 0, s[12:13]
	s_add_i32 m0, s7, 0x4400
	s_mov_b32 s4, 3
	v_lshl_add_u64 v[0:1], v[66:67], 0, 64
	s_add_i32 m0, s7, 0x6000
	s_mov_b32 s8, 0
	v_lshl_add_u64 v[0:1], v[66:67], 0, s[12:13]
	s_add_i32 m0, s7, 0x6400
	s_nop 0
	v_lshl_add_u64 v[0:1], v[64:65], 0, s[62:63]
	s_add_i32 m0, s7, 0x8000
	s_nop 0
	v_lshl_add_u64 v[0:1], v[64:65], 0, s[60:61]
	s_add_i32 m0, s7, 0x8400
	s_nop 0
	v_lshl_add_u64 v[0:1], v[66:67], 0, s[62:63]
	s_add_i32 m0, s7, 0xa000
	s_nop 0
	v_lshl_add_u64 v[0:1], v[66:67], 0, s[60:61]
	s_add_i32 m0, s7, 0xa400
	s_nop 0
	v_lshrrev_b32_e32 v0, 1, v2
	v_and_b32_e32 v0, 6, v0
	v_lshrrev_b32_e64 v0, v0, s9
	s_ashr_i32 s9, s10, 1
	v_bitop3_b32 v0, v0, v68, 3 bitop3:0x6c
	s_and_b32 s10, s10, 64
	s_andn2_b32 s9, s9, 63
	v_lshlrev_b32_e32 v71, 4, v0
	v_or_b32_e32 v0, s10, v69
	v_or_b32_e32 v1, s9, v69
	v_lshlrev_b32_e32 v72, 6, v0
	v_mov_b32_e32 v0, 0
	v_lshlrev_b32_e32 v70, 6, v1
	v_mov_b32_e32 v1, v0
	v_mov_b32_e32 v2, v0
	v_mov_b32_e32 v3, v0
	v_mov_b32_e32 v16, v0
	v_mov_b32_e32 v17, v0
	v_mov_b32_e32 v18, v0
	v_mov_b32_e32 v19, v0
	v_mov_b32_e32 v28, v0
	v_mov_b32_e32 v29, v0
	v_mov_b32_e32 v30, v0
	v_mov_b32_e32 v31, v0
	v_mov_b32_e32 v44, v0
	v_mov_b32_e32 v45, v0
	v_mov_b32_e32 v46, v0
	v_mov_b32_e32 v47, v0
	v_mov_b32_e32 v48, v0
	v_mov_b32_e32 v49, v0
	v_mov_b32_e32 v50, v0
	v_mov_b32_e32 v51, v0
	v_mov_b32_e32 v52, v0
	v_mov_b32_e32 v53, v0
	v_mov_b32_e32 v54, v0
	v_mov_b32_e32 v55, v0
	v_mov_b32_e32 v56, v0
	v_mov_b32_e32 v57, v0
	v_mov_b32_e32 v58, v0
	v_mov_b32_e32 v59, v0
	v_mov_b32_e32 v60, v0
	v_mov_b32_e32 v61, v0
	v_mov_b32_e32 v62, v0
	v_mov_b32_e32 v63, v0
	v_mov_b32_e32 v40, v0
	v_mov_b32_e32 v41, v0
	v_mov_b32_e32 v42, v0
	v_mov_b32_e32 v43, v0
	v_mov_b32_e32 v36, v0
	v_mov_b32_e32 v37, v0
	v_mov_b32_e32 v38, v0
	v_mov_b32_e32 v39, v0
	v_mov_b32_e32 v32, v0
	v_mov_b32_e32 v33, v0
	v_mov_b32_e32 v34, v0
	v_mov_b32_e32 v35, v0
	v_mov_b32_e32 v24, v0
	v_mov_b32_e32 v25, v0
	v_mov_b32_e32 v26, v0
	v_mov_b32_e32 v27, v0
	v_mov_b32_e32 v20, v0
	v_mov_b32_e32 v21, v0
	v_mov_b32_e32 v22, v0
	v_mov_b32_e32 v23, v0
	v_mov_b32_e32 v12, v0
	v_mov_b32_e32 v13, v0
	v_mov_b32_e32 v14, v0
	v_mov_b32_e32 v15, v0
	v_mov_b32_e32 v8, v0
	v_mov_b32_e32 v9, v0
	v_mov_b32_e32 v10, v0
	v_mov_b32_e32 v11, v0
	v_mov_b32_e32 v4, v0
	v_mov_b32_e32 v5, v0
	v_mov_b32_e32 v6, v0
	v_mov_b32_e32 v7, v0
	v_and_b32_e32 v204, 15, v168
	v_lshrrev_b32_e32 v205, 4, v168
	v_bfe_u32 v206, v168, 1, 3
	v_xor_b32_e32 v205, v205, v206
	v_lshlrev_b32_e32 v205, 4, v205
	v_readfirstlane_b32 s13, v162
	v_readfirstlane_b32 s14, v64
	v_readfirstlane_b32 s15, v65
	v_readfirstlane_b32 s16, v66
	v_readfirstlane_b32 s17, v67
	s_lshr_b32 s13, s13, 6
	s_lshr_b32 s28, s13, 1
	s_and_b32 s29, s13, 1
	s_lshl_b32 s28, s28, 6
	v_add_u32_e32 v206, s28, v204
	v_lshl_add_u32 v232, v206, 7, v205
	v_xor_b32_e32 v233, 64, v232
	v_add_u32_e32 v232, 16, v232
	v_add_u32_e32 v233, 16, v233
	v_lshl_add_u32 v206, s29, 6, v204
	v_lshl_add_u32 v234, v206, 7, v205
	v_xor_b32_e32 v235, 64, v234
	v_add_u32_e32 v234, 0x4010, v234
	v_add_u32_e32 v235, 0x4010, v235
	v_lshrrev_b32_e32 v206, 3, v168
	v_and_b32_e32 v207, 7, v168
	v_lshrrev_b32_e32 v204, 1, v206
	v_xor_b32_e32 v207, v207, v204
	v_lshlrev_b32_e32 v207, 4, v207
	v_lshl_add_u32 v236, v206, 11, v207
	v_xor_b32_e32 v237, 64, v236
	v_mov_b32_e32 v238, v236
	v_mov_b32_e32 v239, v237
	s_lshl_b32 s28, s13, 12
	s_lshl_b32 s29, s13, 12
	s_add_i32 m0, s28, 0x10
	s_nop 0
	global_load_lds_dwordx4 v238, s[14:15]
	s_add_i32 m0, s28, 0x410
	s_add_u32 s18, s14, 0x4000
	s_addc_u32 s19, s15, 0
	global_load_lds_dwordx4 v239, s[18:19]
	s_add_i32 m0, s28, 0x810
	s_add_u32 s18, s14, 0x8000
	s_addc_u32 s19, s15, 0
	global_load_lds_dwordx4 v238, s[18:19]
	s_add_i32 m0, s28, 0xc10
	s_add_u32 s18, s14, 0xc000
	s_addc_u32 s19, s15, 0
	global_load_lds_dwordx4 v239, s[18:19]
	s_add_i32 m0, s29, 0x4010
	s_nop 0
	global_load_lds_dwordx4 v236, s[16:17]
	s_add_i32 m0, s29, 0x4410
	s_add_u32 s18, s16, 0x4000
	s_addc_u32 s19, s17, 0
	global_load_lds_dwordx4 v237, s[18:19]
	s_add_i32 m0, s29, 0x4810
	s_add_u32 s18, s16, 0x8000
	s_addc_u32 s19, s17, 0
	global_load_lds_dwordx4 v236, s[18:19]
	s_add_i32 m0, s29, 0x4c10
	s_add_u32 s18, s16, 0xc000
	s_addc_u32 s19, s17, 0
	global_load_lds_dwordx4 v237, s[18:19]
	s_mov_b32 s32, 0
	s_waitcnt vmcnt(0)
	s_barrier
	s_setprio 1
.LBB1_67:
	s_lshl_b32 s13, s32, 8
	s_add_i32 s13, s13, 0x80
	s_min_u32 s13, s13, 0x780
	s_add_u32 s40, s14, s13
	s_addc_u32 s41, s15, 0
	s_add_u32 s42, s16, s13
	s_addc_u32 s43, s17, 0
	ds_read_b128 v[90:93], v234 offset:0
	ds_read_b128 v[94:97], v234 offset:2048
	ds_read_b128 v[98:101], v234 offset:4096
	ds_read_b128 v[102:105], v234 offset:6144
	ds_read_b128 v[74:77], v232 offset:0
	ds_read_b128 v[78:81], v232 offset:2048
	ds_read_b128 v[82:85], v232 offset:4096
	ds_read_b128 v[86:89], v232 offset:6144
	ds_read_b128 v[216:219], v235 offset:0
	ds_read_b128 v[220:223], v235 offset:2048
	ds_read_b128 v[224:227], v235 offset:4096
	ds_read_b128 v[228:231], v235 offset:6144
	ds_read_b128 v[188:191], v233 offset:0
	ds_read_b128 v[192:195], v233 offset:2048
	ds_read_b128 v[196:199], v233 offset:4096
	ds_read_b128 v[200:203], v233 offset:6144
	s_waitcnt lgkmcnt(11)
	s_add_i32 m0, s28, 0x8010
	s_nop 0
	v_mfma_f32_16x16x32_bf16 v[60:63], v[90:93], v[74:77], v[60:63]
	v_mfma_f32_16x16x32_bf16 v[56:59], v[94:97], v[74:77], v[56:59]
	global_load_lds_dwordx4 v238, s[40:41]
	v_mfma_f32_16x16x32_bf16 v[52:55], v[98:101], v[74:77], v[52:55]
	v_mfma_f32_16x16x32_bf16 v[48:51], v[102:105], v[74:77], v[48:51]
	s_waitcnt lgkmcnt(10)
	s_add_i32 m0, s28, 0x8410
	s_add_u32 s18, s40, 0x4000
	s_addc_u32 s19, s41, 0
	v_mfma_f32_16x16x32_bf16 v[44:47], v[90:93], v[78:81], v[44:47]
	v_mfma_f32_16x16x32_bf16 v[28:31], v[94:97], v[78:81], v[28:31]
	global_load_lds_dwordx4 v239, s[18:19]
	v_mfma_f32_16x16x32_bf16 v[16:19], v[98:101], v[78:81], v[16:19]
	v_mfma_f32_16x16x32_bf16 v[0:3], v[102:105], v[78:81], v[0:3]
	s_waitcnt lgkmcnt(9)
	s_add_i32 m0, s28, 0x8810
	s_add_u32 s18, s40, 0x8000
	s_addc_u32 s19, s41, 0
	v_mfma_f32_16x16x32_bf16 v[40:43], v[90:93], v[82:85], v[40:43]
	v_mfma_f32_16x16x32_bf16 v[36:39], v[94:97], v[82:85], v[36:39]
	global_load_lds_dwordx4 v238, s[18:19]
	v_mfma_f32_16x16x32_bf16 v[32:35], v[98:101], v[82:85], v[32:35]
	v_mfma_f32_16x16x32_bf16 v[24:27], v[102:105], v[82:85], v[24:27]
	s_waitcnt lgkmcnt(8)
	s_add_i32 m0, s28, 0x8c10
	s_add_u32 s18, s40, 0xc000
	s_addc_u32 s19, s41, 0
	v_mfma_f32_16x16x32_bf16 v[20:23], v[90:93], v[86:89], v[20:23]
	v_mfma_f32_16x16x32_bf16 v[12:15], v[94:97], v[86:89], v[12:15]
	global_load_lds_dwordx4 v239, s[18:19]
	v_mfma_f32_16x16x32_bf16 v[8:11], v[98:101], v[86:89], v[8:11]
	v_mfma_f32_16x16x32_bf16 v[4:7], v[102:105], v[86:89], v[4:7]
	s_waitcnt lgkmcnt(3)
	s_add_i32 m0, s29, 0xc010
	s_nop 0
	v_mfma_f32_16x16x32_bf16 v[60:63], v[216:219], v[188:191], v[60:63]
	v_mfma_f32_16x16x32_bf16 v[56:59], v[220:223], v[188:191], v[56:59]
	global_load_lds_dwordx4 v236, s[42:43]
	v_mfma_f32_16x16x32_bf16 v[52:55], v[224:227], v[188:191], v[52:55]
	v_mfma_f32_16x16x32_bf16 v[48:51], v[228:231], v[188:191], v[48:51]
	s_waitcnt lgkmcnt(2)
	s_add_i32 m0, s29, 0xc410
	s_add_u32 s18, s42, 0x4000
	s_addc_u32 s19, s43, 0
	v_mfma_f32_16x16x32_bf16 v[44:47], v[216:219], v[192:195], v[44:47]
	v_mfma_f32_16x16x32_bf16 v[28:31], v[220:223], v[192:195], v[28:31]
	global_load_lds_dwordx4 v237, s[18:19]
	v_mfma_f32_16x16x32_bf16 v[16:19], v[224:227], v[192:195], v[16:19]
	v_mfma_f32_16x16x32_bf16 v[0:3], v[228:231], v[192:195], v[0:3]
	s_waitcnt lgkmcnt(1)
	s_add_i32 m0, s29, 0xc810
	s_add_u32 s18, s42, 0x8000
	s_addc_u32 s19, s43, 0
	v_mfma_f32_16x16x32_bf16 v[40:43], v[216:219], v[196:199], v[40:43]
	v_mfma_f32_16x16x32_bf16 v[36:39], v[220:223], v[196:199], v[36:39]
	global_load_lds_dwordx4 v236, s[18:19]
	v_mfma_f32_16x16x32_bf16 v[32:35], v[224:227], v[196:199], v[32:35]
	v_mfma_f32_16x16x32_bf16 v[24:27], v[228:231], v[196:199], v[24:27]
	s_waitcnt lgkmcnt(0)
	s_add_i32 m0, s29, 0xcc10
	s_add_u32 s18, s42, 0xc000
	s_addc_u32 s19, s43, 0
	v_mfma_f32_16x16x32_bf16 v[20:23], v[216:219], v[200:203], v[20:23]
	v_mfma_f32_16x16x32_bf16 v[12:15], v[220:223], v[200:203], v[12:15]
	global_load_lds_dwordx4 v237, s[18:19]
	v_mfma_f32_16x16x32_bf16 v[8:11], v[224:227], v[200:203], v[8:11]
	v_mfma_f32_16x16x32_bf16 v[4:7], v[228:231], v[200:203], v[4:7]
	s_waitcnt vmcnt(0)
	s_barrier
	s_lshl_b32 s13, s32, 8
	s_add_i32 s13, s13, 0x100
	s_min_u32 s13, s13, 0x780
	s_add_u32 s40, s14, s13
	s_addc_u32 s41, s15, 0
	s_add_u32 s42, s16, s13
	s_addc_u32 s43, s17, 0
	ds_read_b128 v[90:93], v234 offset:32768
	ds_read_b128 v[94:97], v234 offset:34816
	ds_read_b128 v[98:101], v234 offset:36864
	ds_read_b128 v[102:105], v234 offset:38912
	ds_read_b128 v[74:77], v232 offset:32768
	ds_read_b128 v[78:81], v232 offset:34816
	ds_read_b128 v[82:85], v232 offset:36864
	ds_read_b128 v[86:89], v232 offset:38912
	ds_read_b128 v[216:219], v235 offset:32768
	ds_read_b128 v[220:223], v235 offset:34816
	ds_read_b128 v[224:227], v235 offset:36864
	ds_read_b128 v[228:231], v235 offset:38912
	ds_read_b128 v[188:191], v233 offset:32768
	ds_read_b128 v[192:195], v233 offset:34816
	ds_read_b128 v[196:199], v233 offset:36864
	ds_read_b128 v[200:203], v233 offset:38912
	s_waitcnt lgkmcnt(11)
	s_add_i32 m0, s28, 0x10
	s_nop 0
	v_mfma_f32_16x16x32_bf16 v[60:63], v[90:93], v[74:77], v[60:63]
	v_mfma_f32_16x16x32_bf16 v[56:59], v[94:97], v[74:77], v[56:59]
	global_load_lds_dwordx4 v238, s[40:41]
	v_mfma_f32_16x16x32_bf16 v[52:55], v[98:101], v[74:77], v[52:55]
	v_mfma_f32_16x16x32_bf16 v[48:51], v[102:105], v[74:77], v[48:51]
	s_waitcnt lgkmcnt(10)
	s_add_i32 m0, s28, 0x410
	s_add_u32 s18, s40, 0x4000
	s_addc_u32 s19, s41, 0
	v_mfma_f32_16x16x32_bf16 v[44:47], v[90:93], v[78:81], v[44:47]
	v_mfma_f32_16x16x32_bf16 v[28:31], v[94:97], v[78:81], v[28:31]
	global_load_lds_dwordx4 v239, s[18:19]
	v_mfma_f32_16x16x32_bf16 v[16:19], v[98:101], v[78:81], v[16:19]
	v_mfma_f32_16x16x32_bf16 v[0:3], v[102:105], v[78:81], v[0:3]
	s_waitcnt lgkmcnt(9)
	s_add_i32 m0, s28, 0x810
	s_add_u32 s18, s40, 0x8000
	s_addc_u32 s19, s41, 0
	v_mfma_f32_16x16x32_bf16 v[40:43], v[90:93], v[82:85], v[40:43]
	v_mfma_f32_16x16x32_bf16 v[36:39], v[94:97], v[82:85], v[36:39]
	global_load_lds_dwordx4 v238, s[18:19]
	v_mfma_f32_16x16x32_bf16 v[32:35], v[98:101], v[82:85], v[32:35]
	v_mfma_f32_16x16x32_bf16 v[24:27], v[102:105], v[82:85], v[24:27]
	s_waitcnt lgkmcnt(8)
	s_add_i32 m0, s28, 0xc10
	s_add_u32 s18, s40, 0xc000
	s_addc_u32 s19, s41, 0
	v_mfma_f32_16x16x32_bf16 v[20:23], v[90:93], v[86:89], v[20:23]
	v_mfma_f32_16x16x32_bf16 v[12:15], v[94:97], v[86:89], v[12:15]
	global_load_lds_dwordx4 v239, s[18:19]
	v_mfma_f32_16x16x32_bf16 v[8:11], v[98:101], v[86:89], v[8:11]
	v_mfma_f32_16x16x32_bf16 v[4:7], v[102:105], v[86:89], v[4:7]
	s_waitcnt lgkmcnt(3)
	s_add_i32 m0, s29, 0x4010
	s_nop 0
	v_mfma_f32_16x16x32_bf16 v[60:63], v[216:219], v[188:191], v[60:63]
	v_mfma_f32_16x16x32_bf16 v[56:59], v[220:223], v[188:191], v[56:59]
	global_load_lds_dwordx4 v236, s[42:43]
	v_mfma_f32_16x16x32_bf16 v[52:55], v[224:227], v[188:191], v[52:55]
	v_mfma_f32_16x16x32_bf16 v[48:51], v[228:231], v[188:191], v[48:51]
	s_waitcnt lgkmcnt(2)
	s_add_i32 m0, s29, 0x4410
	s_add_u32 s18, s42, 0x4000
	s_addc_u32 s19, s43, 0
	v_mfma_f32_16x16x32_bf16 v[44:47], v[216:219], v[192:195], v[44:47]
	v_mfma_f32_16x16x32_bf16 v[28:31], v[220:223], v[192:195], v[28:31]
	global_load_lds_dwordx4 v237, s[18:19]
	v_mfma_f32_16x16x32_bf16 v[16:19], v[224:227], v[192:195], v[16:19]
	v_mfma_f32_16x16x32_bf16 v[0:3], v[228:231], v[192:195], v[0:3]
	s_waitcnt lgkmcnt(1)
	s_add_i32 m0, s29, 0x4810
	s_add_u32 s18, s42, 0x8000
	s_addc_u32 s19, s43, 0
	v_mfma_f32_16x16x32_bf16 v[40:43], v[216:219], v[196:199], v[40:43]
	v_mfma_f32_16x16x32_bf16 v[36:39], v[220:223], v[196:199], v[36:39]
	global_load_lds_dwordx4 v236, s[18:19]
	v_mfma_f32_16x16x32_bf16 v[32:35], v[224:227], v[196:199], v[32:35]
	v_mfma_f32_16x16x32_bf16 v[24:27], v[228:231], v[196:199], v[24:27]
	s_waitcnt lgkmcnt(0)
	s_add_i32 m0, s29, 0x4c10
	s_add_u32 s18, s42, 0xc000
	s_addc_u32 s19, s43, 0
	v_mfma_f32_16x16x32_bf16 v[20:23], v[216:219], v[200:203], v[20:23]
	v_mfma_f32_16x16x32_bf16 v[12:15], v[220:223], v[200:203], v[12:15]
	global_load_lds_dwordx4 v237, s[18:19]
	v_mfma_f32_16x16x32_bf16 v[8:11], v[224:227], v[200:203], v[8:11]
	v_mfma_f32_16x16x32_bf16 v[4:7], v[228:231], v[200:203], v[4:7]
	s_waitcnt vmcnt(0)
	s_barrier
	s_add_i32 s32, s32, 1
	s_cmp_eq_u32 s32, 8
	s_cbranch_scc0 .LBB1_67
	s_setprio 0
	v_or_b32_e32 v64, s6, v69
	v_lshl_or_b32 v65, v68, 2, s5
	s_waitcnt vmcnt(0)
	s_waitcnt vmcnt(0)
	s_barrier
	v_add_u32_e32 v64, s9, v64
	v_or_b32_e32 v66, s10, v65
	s_load_dwordx16 s[4:19], s[0:1], 0x140
	v_ashrrev_i32_e32 v65, 31, v64
	v_lshlrev_b64 v[68:69], 12, v[64:65]
	v_ashrrev_i32_e32 v67, 31, v66
	v_cvt_pk_bf16_f32 v60, v60, v61
	v_cvt_pk_bf16_f32 v61, v62, v63
	s_waitcnt lgkmcnt(0)
	v_lshl_add_u64 v[62:63], s[16:17], 0, v[68:69]
	v_lshlrev_b64 v[66:67], 1, v[66:67]
	v_lshl_add_u64 v[62:63], v[62:63], 0, v[66:67]
	v_cvt_pk_bf16_f32 v48, v48, v49
	v_cvt_pk_bf16_f32 v49, v50, v51
	global_store_dwordx2 v[62:63], v[48:49], off offset:96
	v_or_b32_e32 v48, 16, v64
	v_ashrrev_i32_e32 v49, 31, v48
	v_lshlrev_b64 v[48:49], 12, v[48:49]
	v_cvt_pk_bf16_f32 v44, v44, v45
	v_cvt_pk_bf16_f32 v45, v46, v47
	v_lshl_add_u64 v[46:47], s[16:17], 0, v[48:49]
	v_lshl_add_u64 v[46:47], v[46:47], 0, v[66:67]
	v_cvt_pk_bf16_f32 v0, v0, v1
	v_cvt_pk_bf16_f32 v1, v2, v3
	global_store_dwordx2 v[46:47], v[0:1], off offset:96
	v_or_b32_e32 v0, 32, v64
	v_ashrrev_i32_e32 v1, 31, v0
	v_lshlrev_b64 v[0:1], 12, v[0:1]
	v_lshl_add_u64 v[0:1], s[16:17], 0, v[0:1]
	v_cvt_pk_bf16_f32 v2, v40, v41
	v_cvt_pk_bf16_f32 v3, v42, v43
	v_lshl_add_u64 v[0:1], v[0:1], 0, v[66:67]
	global_store_dwordx2 v[0:1], v[2:3], off
	v_cvt_pk_bf16_f32 v2, v36, v37
	v_cvt_pk_bf16_f32 v3, v38, v39
	global_store_dwordx2 v[0:1], v[2:3], off offset:32
	v_cvt_pk_bf16_f32 v2, v32, v33
	v_cvt_pk_bf16_f32 v3, v34, v35
	global_store_dwordx2 v[0:1], v[2:3], off offset:64
	v_cvt_pk_bf16_f32 v2, v24, v25
	v_cvt_pk_bf16_f32 v3, v26, v27
	global_store_dwordx2 v[0:1], v[2:3], off offset:96
	v_or_b32_e32 v0, 48, v64
	v_ashrrev_i32_e32 v1, 31, v0
	v_lshlrev_b64 v[0:1], 12, v[0:1]
	v_lshl_add_u64 v[0:1], s[16:17], 0, v[0:1]
	v_cvt_pk_bf16_f32 v2, v20, v21
	v_cvt_pk_bf16_f32 v3, v22, v23
	v_lshl_add_u64 v[0:1], v[0:1], 0, v[66:67]
	global_store_dwordx2 v[0:1], v[2:3], off
	v_cvt_pk_bf16_f32 v2, v12, v13
	v_cvt_pk_bf16_f32 v3, v14, v15
	global_store_dwordx2 v[0:1], v[2:3], off offset:32
	v_cvt_pk_bf16_f32 v2, v8, v9
	v_cvt_pk_bf16_f32 v3, v10, v11
	v_cvt_pk_bf16_f32 v56, v56, v57
	v_cvt_pk_bf16_f32 v57, v58, v59
	v_cvt_pk_bf16_f32 v52, v52, v53
	v_cvt_pk_bf16_f32 v53, v54, v55
	v_cvt_pk_bf16_f32 v28, v28, v29
	v_cvt_pk_bf16_f32 v29, v30, v31
	v_cvt_pk_bf16_f32 v16, v16, v17
	v_cvt_pk_bf16_f32 v17, v18, v19
	global_store_dwordx2 v[0:1], v[2:3], off offset:64
	v_cvt_pk_bf16_f32 v2, v4, v5
	v_cvt_pk_bf16_f32 v3, v6, v7
	global_store_dwordx2 v[62:63], v[60:61], off
	global_store_dwordx2 v[62:63], v[56:57], off offset:32
	global_store_dwordx2 v[62:63], v[52:53], off offset:64
	global_store_dwordx2 v[46:47], v[44:45], off
	global_store_dwordx2 v[46:47], v[28:29], off offset:32
	global_store_dwordx2 v[46:47], v[16:17], off offset:64
	global_store_dwordx2 v[0:1], v[2:3], off offset:96
	s_load_dwordx8 s[80:87], s[0:1], 0x180
	s_add_i32 s2, s2, 1
	s_mov_b64 s[40:41], 0
	s_branch .LBB1_64

.LBB1_1384:
	s_waitcnt lgkmcnt(0)
	v_mov_b32_e32 v2, v162
	s_lshl_b32 s7, s5, 7
	v_readfirstlane_b32 s11, v2
	s_ashr_i32 s8, s11, 6
	v_bfe_u32 v0, v2, 2, 4
	v_lshrrev_b32_e32 v1, 3, v2
	s_addk_i32 s7, 0x3f00
	v_and_b32_e32 v1, 6, v1
	s_movk_i32 s9, 0x78
	v_lshl_or_b32 v4, s8, 5, v0
	v_lshrrev_b32_e64 v1, v1, s9
	v_add_u32_e32 v0, s7, v4
	v_xor_b32_e32 v3, v1, v2
	v_ashrrev_i32_e32 v1, 31, v0
	v_lshlrev_b64 v[0:1], 11, v[0:1]
	v_lshlrev_b32_e32 v3, 4, v3
	s_load_dwordx16 s[80:95], s[0:1], 0xc0
	s_lshl_b32 s6, s4, 7
	v_lshl_add_u64 v[0:1], s[74:75], 0, v[0:1]
	v_and_b32_e32 v128, 48, v3
	v_lshl_add_u64 v[64:65], v[0:1], 0, v[128:129]
	v_add_u32_e32 v0, s6, v4
	v_ashrrev_i32_e32 v1, 31, v0
	s_lshl_b32 s8, s8, 11
	v_lshlrev_b64 v[0:1], 11, v[0:1]
	s_add_i32 s8, s8, 16
	s_waitcnt lgkmcnt(0)
	v_lshl_add_u64 v[0:1], s[84:85], 0, v[0:1]
	s_mov_b32 m0, s8
	v_lshl_add_u64 v[66:67], v[0:1], 0, v[128:129]
	s_barrier
	v_lshl_add_u64 v[0:1], v[64:65], 0, s[34:35]
	s_add_i32 m0, s8, 0x400
	s_mov_b64 s[12:13], 0x8040
	s_add_i32 m0, s8, 0x2000
	v_lshl_add_u64 v[0:1], v[66:67], 0, s[34:35]
	s_add_i32 m0, s8, 0x2400
	v_bfe_u32 v69, v2, 4, 2
	v_lshl_add_u64 v[0:1], v[64:65], 0, 64
	s_add_i32 m0, s8, 0x4000
	v_and_b32_e32 v68, 15, v2
	v_lshl_add_u64 v[0:1], v[64:65], 0, s[12:13]
	s_add_i32 m0, s8, 0x4400
	v_mov_b32_e32 v32, 0
	v_lshl_add_u64 v[0:1], v[66:67], 0, 64
	s_add_i32 m0, s8, 0x6000
	s_mov_b32 s10, 3
	v_lshl_add_u64 v[0:1], v[66:67], 0, s[12:13]
	s_add_i32 m0, s8, 0x6400
	s_mov_b32 s12, 0
	v_lshl_add_u64 v[0:1], v[64:65], 0, s[62:63]
	s_add_i32 m0, s8, 0x8000
	v_mov_b32_e32 v33, v32
	v_lshl_add_u64 v[0:1], v[64:65], 0, s[60:61]
	s_add_i32 m0, s8, 0x8400
	v_mov_b32_e32 v34, v32
	v_lshl_add_u64 v[0:1], v[66:67], 0, s[62:63]
	s_add_i32 m0, s8, 0xa000
	v_mov_b32_e32 v35, v32
	v_lshl_add_u64 v[0:1], v[66:67], 0, s[60:61]
	s_add_i32 m0, s8, 0xa400
	v_mov_b32_e32 v36, v32
	v_lshrrev_b32_e32 v0, 1, v2
	v_and_b32_e32 v0, 6, v0
	v_lshrrev_b32_e64 v0, v0, s9
	s_ashr_i32 s9, s11, 1
	s_andn2_b32 s9, s9, 63
	v_bitop3_b32 v0, v0, v69, 3 bitop3:0x6c
	s_and_b32 s11, s11, 64
	v_or_b32_e32 v1, s9, v68
	v_lshlrev_b32_e32 v71, 4, v0
	v_or_b32_e32 v0, s11, v68
	v_lshlrev_b32_e32 v70, 6, v1
	v_lshlrev_b32_e32 v72, 6, v0
	v_mov_b32_e32 v37, v32
	v_mov_b32_e32 v38, v32
	v_mov_b32_e32 v39, v32
	v_mov_b32_e32 v40, v32
	v_mov_b32_e32 v41, v32
	v_mov_b32_e32 v42, v32
	v_mov_b32_e32 v43, v32
	v_mov_b32_e32 v44, v32
	v_mov_b32_e32 v45, v32
	v_mov_b32_e32 v46, v32
	v_mov_b32_e32 v47, v32
	v_mov_b32_e32 v48, v32
	v_mov_b32_e32 v49, v32
	v_mov_b32_e32 v50, v32
	v_mov_b32_e32 v51, v32
	v_mov_b32_e32 v52, v32
	v_mov_b32_e32 v53, v32
	v_mov_b32_e32 v54, v32
	v_mov_b32_e32 v55, v32
	v_mov_b32_e32 v56, v32
	v_mov_b32_e32 v57, v32
	v_mov_b32_e32 v58, v32
	v_mov_b32_e32 v59, v32
	v_mov_b32_e32 v60, v32
	v_mov_b32_e32 v61, v32
	v_mov_b32_e32 v62, v32
	v_mov_b32_e32 v63, v32
	v_mov_b32_e32 v28, v32
	v_mov_b32_e32 v29, v32
	v_mov_b32_e32 v30, v32
	v_mov_b32_e32 v31, v32
	v_mov_b32_e32 v24, v32
	v_mov_b32_e32 v25, v32
	v_mov_b32_e32 v26, v32
	v_mov_b32_e32 v27, v32
	v_mov_b32_e32 v20, v32
	v_mov_b32_e32 v21, v32
	v_mov_b32_e32 v22, v32
	v_mov_b32_e32 v23, v32
	v_mov_b32_e32 v16, v32
	v_mov_b32_e32 v17, v32
	v_mov_b32_e32 v18, v32
	v_mov_b32_e32 v19, v32
	v_mov_b32_e32 v12, v32
	v_mov_b32_e32 v13, v32
	v_mov_b32_e32 v14, v32
	v_mov_b32_e32 v15, v32
	v_mov_b32_e32 v8, v32
	v_mov_b32_e32 v9, v32
	v_mov_b32_e32 v10, v32
	v_mov_b32_e32 v11, v32
	v_mov_b32_e32 v4, v32
	v_mov_b32_e32 v5, v32
	v_mov_b32_e32 v6, v32
	v_mov_b32_e32 v7, v32
	v_mov_b32_e32 v0, v32
	v_mov_b32_e32 v1, v32
	v_mov_b32_e32 v2, v32
	v_mov_b32_e32 v3, v32
	v_and_b32_e32 v204, 15, v168
	v_lshrrev_b32_e32 v205, 4, v168
	v_bfe_u32 v206, v168, 1, 3
	v_xor_b32_e32 v205, v205, v206
	v_lshlrev_b32_e32 v205, 4, v205
	v_readfirstlane_b32 s13, v162
	v_readfirstlane_b32 s14, v64
	v_readfirstlane_b32 s15, v65
	v_readfirstlane_b32 s16, v66
	v_readfirstlane_b32 s17, v67
	s_lshr_b32 s13, s13, 6
	s_lshr_b32 s28, s13, 1
	s_and_b32 s29, s13, 1
	s_lshl_b32 s28, s28, 6
	v_add_u32_e32 v206, s28, v204
	v_lshl_add_u32 v232, v206, 7, v205
	v_xor_b32_e32 v233, 64, v232
	v_add_u32_e32 v232, 16, v232
	v_add_u32_e32 v233, 16, v233
	v_lshl_add_u32 v206, s29, 6, v204
	v_lshl_add_u32 v234, v206, 7, v205
	v_xor_b32_e32 v235, 64, v234
	v_add_u32_e32 v234, 0x4010, v234
	v_add_u32_e32 v235, 0x4010, v235
	v_lshrrev_b32_e32 v206, 3, v168
	v_and_b32_e32 v207, 7, v168
	v_lshrrev_b32_e32 v204, 1, v206
	v_xor_b32_e32 v207, v207, v204
	v_lshlrev_b32_e32 v207, 4, v207
	v_lshl_add_u32 v236, v206, 11, v207
	v_xor_b32_e32 v237, 64, v236
	v_mov_b32_e32 v238, v236
	v_mov_b32_e32 v239, v237
	s_lshl_b32 s28, s13, 12
	s_lshl_b32 s29, s13, 12
	s_add_i32 m0, s28, 0x10
	s_nop 0
	global_load_lds_dwordx4 v238, s[14:15]
	s_add_i32 m0, s28, 0x410
	s_add_u32 s18, s14, 0x4000
	s_addc_u32 s19, s15, 0
	global_load_lds_dwordx4 v239, s[18:19]
	s_add_i32 m0, s28, 0x810
	s_add_u32 s18, s14, 0x8000
	s_addc_u32 s19, s15, 0
	global_load_lds_dwordx4 v238, s[18:19]
	s_add_i32 m0, s28, 0xc10
	s_add_u32 s18, s14, 0xc000
	s_addc_u32 s19, s15, 0
	global_load_lds_dwordx4 v239, s[18:19]
	s_add_i32 m0, s29, 0x4010
	s_nop 0
	global_load_lds_dwordx4 v236, s[16:17]
	s_add_i32 m0, s29, 0x4410
	s_add_u32 s18, s16, 0x4000
	s_addc_u32 s19, s17, 0
	global_load_lds_dwordx4 v237, s[18:19]
	s_add_i32 m0, s29, 0x4810
	s_add_u32 s18, s16, 0x8000
	s_addc_u32 s19, s17, 0
	global_load_lds_dwordx4 v236, s[18:19]
	s_add_i32 m0, s29, 0x4c10
	s_add_u32 s18, s16, 0xc000
	s_addc_u32 s19, s17, 0
	global_load_lds_dwordx4 v237, s[18:19]
	s_mov_b32 s32, 0
	s_waitcnt vmcnt(0)
	s_barrier
	s_setprio 1
.LBB1_1385:
	s_lshl_b32 s13, s32, 8
	s_add_i32 s13, s13, 0x80
	s_min_u32 s13, s13, 0x780
	s_add_u32 s40, s14, s13
	s_addc_u32 s41, s15, 0
	s_add_u32 s42, s16, s13
	s_addc_u32 s43, s17, 0
	ds_read_b128 v[90:93], v234 offset:0
	ds_read_b128 v[94:97], v234 offset:2048
	ds_read_b128 v[98:101], v234 offset:4096
	ds_read_b128 v[102:105], v234 offset:6144
	ds_read_b128 v[74:77], v232 offset:0
	ds_read_b128 v[78:81], v232 offset:2048
	ds_read_b128 v[82:85], v232 offset:4096
	ds_read_b128 v[86:89], v232 offset:6144
	ds_read_b128 v[216:219], v235 offset:0
	ds_read_b128 v[220:223], v235 offset:2048
	ds_read_b128 v[224:227], v235 offset:4096
	ds_read_b128 v[228:231], v235 offset:6144
	ds_read_b128 v[188:191], v233 offset:0
	ds_read_b128 v[192:195], v233 offset:2048
	ds_read_b128 v[196:199], v233 offset:4096
	ds_read_b128 v[200:203], v233 offset:6144
	s_waitcnt lgkmcnt(11)
	s_add_i32 m0, s28, 0x8010
	s_nop 0
	v_mfma_f32_16x16x32_bf16 v[60:63], v[90:93], v[74:77], v[60:63]
	v_mfma_f32_16x16x32_bf16 v[56:59], v[94:97], v[74:77], v[56:59]
	global_load_lds_dwordx4 v238, s[40:41]
	v_mfma_f32_16x16x32_bf16 v[52:55], v[98:101], v[74:77], v[52:55]
	v_mfma_f32_16x16x32_bf16 v[48:51], v[102:105], v[74:77], v[48:51]
	s_waitcnt lgkmcnt(10)
	s_add_i32 m0, s28, 0x8410
	s_add_u32 s18, s40, 0x4000
	s_addc_u32 s19, s41, 0
	v_mfma_f32_16x16x32_bf16 v[44:47], v[90:93], v[78:81], v[44:47]
	v_mfma_f32_16x16x32_bf16 v[40:43], v[94:97], v[78:81], v[40:43]
	global_load_lds_dwordx4 v239, s[18:19]
	v_mfma_f32_16x16x32_bf16 v[36:39], v[98:101], v[78:81], v[36:39]
	v_mfma_f32_16x16x32_bf16 v[32:35], v[102:105], v[78:81], v[32:35]
	s_waitcnt lgkmcnt(9)
	s_add_i32 m0, s28, 0x8810
	s_add_u32 s18, s40, 0x8000
	s_addc_u32 s19, s41, 0
	v_mfma_f32_16x16x32_bf16 v[28:31], v[90:93], v[82:85], v[28:31]
	v_mfma_f32_16x16x32_bf16 v[24:27], v[94:97], v[82:85], v[24:27]
	global_load_lds_dwordx4 v238, s[18:19]
	v_mfma_f32_16x16x32_bf16 v[20:23], v[98:101], v[82:85], v[20:23]
	v_mfma_f32_16x16x32_bf16 v[16:19], v[102:105], v[82:85], v[16:19]
	s_waitcnt lgkmcnt(8)
	s_add_i32 m0, s28, 0x8c10
	s_add_u32 s18, s40, 0xc000
	s_addc_u32 s19, s41, 0
	v_mfma_f32_16x16x32_bf16 v[12:15], v[90:93], v[86:89], v[12:15]
	v_mfma_f32_16x16x32_bf16 v[8:11], v[94:97], v[86:89], v[8:11]
	global_load_lds_dwordx4 v239, s[18:19]
	v_mfma_f32_16x16x32_bf16 v[4:7], v[98:101], v[86:89], v[4:7]
	v_mfma_f32_16x16x32_bf16 v[0:3], v[102:105], v[86:89], v[0:3]
	s_waitcnt lgkmcnt(3)
	s_add_i32 m0, s29, 0xc010
	s_nop 0
	v_mfma_f32_16x16x32_bf16 v[60:63], v[216:219], v[188:191], v[60:63]
	v_mfma_f32_16x16x32_bf16 v[56:59], v[220:223], v[188:191], v[56:59]
	global_load_lds_dwordx4 v236, s[42:43]
	v_mfma_f32_16x16x32_bf16 v[52:55], v[224:227], v[188:191], v[52:55]
	v_mfma_f32_16x16x32_bf16 v[48:51], v[228:231], v[188:191], v[48:51]
	s_waitcnt lgkmcnt(2)
	s_add_i32 m0, s29, 0xc410
	s_add_u32 s18, s42, 0x4000
	s_addc_u32 s19, s43, 0
	v_mfma_f32_16x16x32_bf16 v[44:47], v[216:219], v[192:195], v[44:47]
	v_mfma_f32_16x16x32_bf16 v[40:43], v[220:223], v[192:195], v[40:43]
	global_load_lds_dwordx4 v237, s[18:19]
	v_mfma_f32_16x16x32_bf16 v[36:39], v[224:227], v[192:195], v[36:39]
	v_mfma_f32_16x16x32_bf16 v[32:35], v[228:231], v[192:195], v[32:35]
	s_waitcnt lgkmcnt(1)
	s_add_i32 m0, s29, 0xc810
	s_add_u32 s18, s42, 0x8000
	s_addc_u32 s19, s43, 0
	v_mfma_f32_16x16x32_bf16 v[28:31], v[216:219], v[196:199], v[28:31]
	v_mfma_f32_16x16x32_bf16 v[24:27], v[220:223], v[196:199], v[24:27]
	global_load_lds_dwordx4 v236, s[18:19]
	v_mfma_f32_16x16x32_bf16 v[20:23], v[224:227], v[196:199], v[20:23]
	v_mfma_f32_16x16x32_bf16 v[16:19], v[228:231], v[196:199], v[16:19]
	s_waitcnt lgkmcnt(0)
	s_add_i32 m0, s29, 0xcc10
	s_add_u32 s18, s42, 0xc000
	s_addc_u32 s19, s43, 0
	v_mfma_f32_16x16x32_bf16 v[12:15], v[216:219], v[200:203], v[12:15]
	v_mfma_f32_16x16x32_bf16 v[8:11], v[220:223], v[200:203], v[8:11]
	global_load_lds_dwordx4 v237, s[18:19]
	v_mfma_f32_16x16x32_bf16 v[4:7], v[224:227], v[200:203], v[4:7]
	v_mfma_f32_16x16x32_bf16 v[0:3], v[228:231], v[200:203], v[0:3]
	s_waitcnt vmcnt(0)
	s_barrier
	s_lshl_b32 s13, s32, 8
	s_add_i32 s13, s13, 0x100
	s_min_u32 s13, s13, 0x780
	s_add_u32 s40, s14, s13
	s_addc_u32 s41, s15, 0
	s_add_u32 s42, s16, s13
	s_addc_u32 s43, s17, 0
	ds_read_b128 v[90:93], v234 offset:32768
	ds_read_b128 v[94:97], v234 offset:34816
	ds_read_b128 v[98:101], v234 offset:36864
	ds_read_b128 v[102:105], v234 offset:38912
	ds_read_b128 v[74:77], v232 offset:32768
	ds_read_b128 v[78:81], v232 offset:34816
	ds_read_b128 v[82:85], v232 offset:36864
	ds_read_b128 v[86:89], v232 offset:38912
	ds_read_b128 v[216:219], v235 offset:32768
	ds_read_b128 v[220:223], v235 offset:34816
	ds_read_b128 v[224:227], v235 offset:36864
	ds_read_b128 v[228:231], v235 offset:38912
	ds_read_b128 v[188:191], v233 offset:32768
	ds_read_b128 v[192:195], v233 offset:34816
	ds_read_b128 v[196:199], v233 offset:36864
	ds_read_b128 v[200:203], v233 offset:38912
	s_waitcnt lgkmcnt(11)
	s_add_i32 m0, s28, 0x10
	s_nop 0
	v_mfma_f32_16x16x32_bf16 v[60:63], v[90:93], v[74:77], v[60:63]
	v_mfma_f32_16x16x32_bf16 v[56:59], v[94:97], v[74:77], v[56:59]
	global_load_lds_dwordx4 v238, s[40:41]
	v_mfma_f32_16x16x32_bf16 v[52:55], v[98:101], v[74:77], v[52:55]
	v_mfma_f32_16x16x32_bf16 v[48:51], v[102:105], v[74:77], v[48:51]
	s_waitcnt lgkmcnt(10)
	s_add_i32 m0, s28, 0x410
	s_add_u32 s18, s40, 0x4000
	s_addc_u32 s19, s41, 0
	v_mfma_f32_16x16x32_bf16 v[44:47], v[90:93], v[78:81], v[44:47]
	v_mfma_f32_16x16x32_bf16 v[40:43], v[94:97], v[78:81], v[40:43]
	global_load_lds_dwordx4 v239, s[18:19]
	v_mfma_f32_16x16x32_bf16 v[36:39], v[98:101], v[78:81], v[36:39]
	v_mfma_f32_16x16x32_bf16 v[32:35], v[102:105], v[78:81], v[32:35]
	s_waitcnt lgkmcnt(9)
	s_add_i32 m0, s28, 0x810
	s_add_u32 s18, s40, 0x8000
	s_addc_u32 s19, s41, 0
	v_mfma_f32_16x16x32_bf16 v[28:31], v[90:93], v[82:85], v[28:31]
	v_mfma_f32_16x16x32_bf16 v[24:27], v[94:97], v[82:85], v[24:27]
	global_load_lds_dwordx4 v238, s[18:19]
	v_mfma_f32_16x16x32_bf16 v[20:23], v[98:101], v[82:85], v[20:23]
	v_mfma_f32_16x16x32_bf16 v[16:19], v[102:105], v[82:85], v[16:19]
	s_waitcnt lgkmcnt(8)
	s_add_i32 m0, s28, 0xc10
	s_add_u32 s18, s40, 0xc000
	s_addc_u32 s19, s41, 0
	v_mfma_f32_16x16x32_bf16 v[12:15], v[90:93], v[86:89], v[12:15]
	v_mfma_f32_16x16x32_bf16 v[8:11], v[94:97], v[86:89], v[8:11]
	global_load_lds_dwordx4 v239, s[18:19]
	v_mfma_f32_16x16x32_bf16 v[4:7], v[98:101], v[86:89], v[4:7]
	v_mfma_f32_16x16x32_bf16 v[0:3], v[102:105], v[86:89], v[0:3]
	s_waitcnt lgkmcnt(3)
	s_add_i32 m0, s29, 0x4010
	s_nop 0
	v_mfma_f32_16x16x32_bf16 v[60:63], v[216:219], v[188:191], v[60:63]
	v_mfma_f32_16x16x32_bf16 v[56:59], v[220:223], v[188:191], v[56:59]
	global_load_lds_dwordx4 v236, s[42:43]
	v_mfma_f32_16x16x32_bf16 v[52:55], v[224:227], v[188:191], v[52:55]
	v_mfma_f32_16x16x32_bf16 v[48:51], v[228:231], v[188:191], v[48:51]
	s_waitcnt lgkmcnt(2)
	s_add_i32 m0, s29, 0x4410
	s_add_u32 s18, s42, 0x4000
	s_addc_u32 s19, s43, 0
	v_mfma_f32_16x16x32_bf16 v[44:47], v[216:219], v[192:195], v[44:47]
	v_mfma_f32_16x16x32_bf16 v[40:43], v[220:223], v[192:195], v[40:43]
	global_load_lds_dwordx4 v237, s[18:19]
	v_mfma_f32_16x16x32_bf16 v[36:39], v[224:227], v[192:195], v[36:39]
	v_mfma_f32_16x16x32_bf16 v[32:35], v[228:231], v[192:195], v[32:35]
	s_waitcnt lgkmcnt(1)
	s_add_i32 m0, s29, 0x4810
	s_add_u32 s18, s42, 0x8000
	s_addc_u32 s19, s43, 0
	v_mfma_f32_16x16x32_bf16 v[28:31], v[216:219], v[196:199], v[28:31]
	v_mfma_f32_16x16x32_bf16 v[24:27], v[220:223], v[196:199], v[24:27]
	global_load_lds_dwordx4 v236, s[18:19]
	v_mfma_f32_16x16x32_bf16 v[20:23], v[224:227], v[196:199], v[20:23]
	v_mfma_f32_16x16x32_bf16 v[16:19], v[228:231], v[196:199], v[16:19]
	s_waitcnt lgkmcnt(0)
	s_add_i32 m0, s29, 0x4c10
	s_add_u32 s18, s42, 0xc000
	s_addc_u32 s19, s43, 0
	v_mfma_f32_16x16x32_bf16 v[12:15], v[216:219], v[200:203], v[12:15]
	v_mfma_f32_16x16x32_bf16 v[8:11], v[220:223], v[200:203], v[8:11]
	global_load_lds_dwordx4 v237, s[18:19]
	v_mfma_f32_16x16x32_bf16 v[4:7], v[224:227], v[200:203], v[4:7]
	v_mfma_f32_16x16x32_bf16 v[0:3], v[228:231], v[200:203], v[0:3]
	s_waitcnt vmcnt(0)
	s_barrier
	s_add_i32 s32, s32, 1
	s_cmp_eq_u32 s32, 8
	s_cbranch_scc0 .LBB1_1385
	s_setprio 0
	v_or_b32_e32 v64, s7, v68
	s_waitcnt vmcnt(0)
	v_add_u32_e32 v66, s9, v64
	v_lshl_or_b32 v64, v69, 2, s6
	v_or_b32_e32 v64, s11, v64
	v_lshlrev_b32_e32 v68, 5, v66
	s_movk_i32 s6, 0x1fff
	v_ashrrev_i32_e32 v69, 31, v68
	v_cmp_lt_i32_e32 vcc, s6, v64
	s_waitcnt vmcnt(0)
	s_barrier
	s_and_saveexec_b64 s[6:7], vcc
	s_load_dwordx8 s[80:87], s[0:1], 0x180
	s_xor_b64 s[30:31], exec, s[6:7]
	s_movk_i32 s10, 0x2020
	s_cbranch_execz .LBB1_1390
	v_cmp_gt_u32_e64 s[38:39], s10, v64
	s_and_saveexec_b64 s[40:41], s[38:39]
	s_cbranch_execz .LBB1_1389
	v_add_u32_e32 v128, 0xffffe000, v64
	v_lshl_add_u64 v[70:71], v[68:69], 2, s[78:79]
	v_lshlrev_b64 v[72:73], 2, v[128:129]
	v_lshl_add_u64 v[74:75], v[70:71], 0, v[72:73]
	v_lshl_add_u64 v[70:71], s[22:23], 0, v[72:73]
	global_load_dwordx4 v[70:73], v[70:71], off
	s_waitcnt vmcnt(0)
	v_pk_add_f32 v[72:73], v[62:63], v[72:73]
	v_pk_add_f32 v[70:71], v[60:61], v[70:71]
	global_store_dwordx4 v[74:75], v[70:73], off
